# sc8 + P5 MFMA blocks at s_setprio 1 (single raise after the pre-MFMA barrier, single drop before the post-MFMA barrier)
# speedup vs baseline: 1.0110x; 1.0047x over previous
.LBB0_872:
	s_add_i32 s77, s52, 2
	s_add_u32 s50, s34, 0xfffc0080
	s_addc_u32 s51, s35, -1
	s_cmp_eq_u32 s70, s52
	s_cselect_b32 s52, s30, s21
	s_cselect_b32 s55, s29, s51
	s_cselect_b32 s54, s28, s50
	s_cselect_b32 s53, s31, s23
	ds_read_b128 v[150:153], v246
	ds_read_b128 v[154:157], v246 offset:1024
	ds_read_b128 v[158:161], v246 offset:2048
	ds_read_b128 v[162:165], v246 offset:3072
	ds_read_b128 v[166:169], v247
	ds_read_b128 v[170:173], v247 offset:1024
	ds_read_b128 v[174:177], v247 offset:2048
	ds_read_b128 v[178:181], v247 offset:3072
	ds_read_b128 v[182:185], v149
	ds_read_b128 v[186:189], v149 offset:1024
	ds_read_b128 v[190:193], v149 offset:2048
	ds_read_b128 v[194:197], v149 offset:3072
	ds_read_b128 v[198:201], v149 offset:4096
	ds_read_b128 v[202:205], v149 offset:5120
	ds_read_b128 v[206:209], v149 offset:6144
	ds_read_b128 v[210:213], v149 offset:7168
	s_add_i32 m0, s60, 0xc000
	s_nop 0
	global_load_lds_dwordx4 v132, s[34:35]
	s_add_i32 m0, s60, 0xe000
	s_nop 0
	global_load_lds_dwordx4 v134, s[34:35]
	s_waitcnt vmcnt(8)
	s_waitcnt lgkmcnt(0)
	s_barrier
	s_setprio 1
	v_mfma_f32_16x16x32_bf16 v[78:81], v[150:153], v[182:185], v[78:81]
	v_mfma_f32_16x16x32_bf16 v[78:81], v[154:157], v[186:189], v[78:81]
	v_mfma_f32_16x16x32_bf16 v[66:69], v[154:157], v[194:197], v[66:69]
	v_mfma_f32_16x16x32_bf16 v[66:69], v[150:153], v[190:193], v[66:69]
	v_mfma_f32_16x16x32_bf16 v[70:73], v[150:153], v[198:201], v[70:73]
	v_mfma_f32_16x16x32_bf16 v[70:73], v[154:157], v[202:205], v[70:73]
	v_mfma_f32_16x16x32_bf16 v[74:77], v[154:157], v[210:213], v[74:77]
	v_mfma_f32_16x16x32_bf16 v[74:77], v[150:153], v[206:209], v[74:77]
	v_mfma_f32_16x16x32_bf16 v[10:13], v[158:161], v[206:209], v[10:13]
	v_mfma_f32_16x16x32_bf16 v[10:13], v[162:165], v[210:213], v[10:13]
	v_mfma_f32_16x16x32_bf16 v[6:9], v[162:165], v[202:205], v[6:9]
	v_mfma_f32_16x16x32_bf16 v[6:9], v[158:161], v[198:201], v[6:9]
	v_mfma_f32_16x16x32_bf16 v[2:5], v[158:161], v[190:193], v[2:5]
	v_mfma_f32_16x16x32_bf16 v[2:5], v[162:165], v[194:197], v[2:5]
	v_mfma_f32_16x16x32_bf16 v[14:17], v[162:165], v[186:189], v[14:17]
	v_mfma_f32_16x16x32_bf16 v[14:17], v[158:161], v[182:185], v[14:17]
	v_mfma_f32_16x16x32_bf16 v[98:101], v[166:169], v[182:185], v[98:101]
	v_mfma_f32_16x16x32_bf16 v[98:101], v[170:173], v[186:189], v[98:101]
	v_mfma_f32_16x16x32_bf16 v[82:85], v[170:173], v[194:197], v[82:85]
	v_mfma_f32_16x16x32_bf16 v[82:85], v[166:169], v[190:193], v[82:85]
	v_mfma_f32_16x16x32_bf16 v[86:89], v[166:169], v[198:201], v[86:89]
	v_mfma_f32_16x16x32_bf16 v[86:89], v[170:173], v[202:205], v[86:89]
	v_mfma_f32_16x16x32_bf16 v[94:97], v[170:173], v[210:213], v[94:97]
	v_mfma_f32_16x16x32_bf16 v[94:97], v[166:169], v[206:209], v[94:97]
	v_mfma_f32_16x16x32_bf16 v[30:33], v[174:177], v[206:209], v[30:33]
	v_mfma_f32_16x16x32_bf16 v[30:33], v[178:181], v[210:213], v[30:33]
	v_mfma_f32_16x16x32_bf16 v[22:25], v[178:181], v[202:205], v[22:25]
	v_mfma_f32_16x16x32_bf16 v[22:25], v[174:177], v[198:201], v[22:25]
	v_mfma_f32_16x16x32_bf16 v[18:21], v[174:177], v[190:193], v[18:21]
	v_mfma_f32_16x16x32_bf16 v[18:21], v[178:181], v[194:197], v[18:21]
	v_mfma_f32_16x16x32_bf16 v[34:37], v[178:181], v[186:189], v[34:37]
	v_mfma_f32_16x16x32_bf16 v[34:37], v[174:177], v[182:185], v[34:37]
	s_setprio 0
	s_barrier
	ds_read_b128 v[182:185], v149 offset:16384
	ds_read_b128 v[186:189], v149 offset:17408
	ds_read_b128 v[190:193], v149 offset:18432
	ds_read_b128 v[194:197], v149 offset:19456
	ds_read_b128 v[198:201], v149 offset:20480
	ds_read_b128 v[202:205], v149 offset:21504
	ds_read_b128 v[206:209], v149 offset:22528
	ds_read_b128 v[210:213], v149 offset:23552
	s_add_i32 s50, s73, s15
	s_mov_b32 m0, s50
	s_nop 0
	global_load_lds_dwordx4 v228, s[52:53]
	s_add_i32 m0, s50, 0x2000
	s_add_u32 s50, s52, 0x40000
	s_addc_u32 s51, s53, 0
	s_add_i32 s78, s74, s15
	global_load_lds_dwordx4 v232, s[52:53]
	s_mov_b32 m0, s78
	s_nop 0
	global_load_lds_dwordx4 v228, s[50:51]
	s_add_i32 m0, s78, 0x2000
	s_nop 0
	global_load_lds_dwordx4 v232, s[50:51]
	s_mov_b32 m0, s60
	s_nop 0
	global_load_lds_dwordx4 v226, s[54:55]
	s_mov_b32 m0, s61
	s_nop 0
	global_load_lds_dwordx4 v230, s[54:55]
	s_waitcnt vmcnt(8)
	s_waitcnt lgkmcnt(0)
	s_barrier
	s_setprio 1
	v_mfma_f32_16x16x32_bf16 v[90:93], v[150:153], v[182:185], v[90:93]
	v_mfma_f32_16x16x32_bf16 v[90:93], v[154:157], v[186:189], v[90:93]
	v_mfma_f32_16x16x32_bf16 v[102:105], v[154:157], v[194:197], v[102:105]
	v_mfma_f32_16x16x32_bf16 v[102:105], v[150:153], v[190:193], v[102:105]
	v_mfma_f32_16x16x32_bf16 v[106:109], v[150:153], v[198:201], v[106:109]
	v_mfma_f32_16x16x32_bf16 v[106:109], v[154:157], v[202:205], v[106:109]
	v_mfma_f32_16x16x32_bf16 v[110:113], v[154:157], v[210:213], v[110:113]
	v_mfma_f32_16x16x32_bf16 v[110:113], v[150:153], v[206:209], v[110:113]
	v_mfma_f32_16x16x32_bf16 v[46:49], v[158:161], v[206:209], v[46:49]
	v_mfma_f32_16x16x32_bf16 v[46:49], v[162:165], v[210:213], v[46:49]
	v_mfma_f32_16x16x32_bf16 v[42:45], v[162:165], v[202:205], v[42:45]
	v_mfma_f32_16x16x32_bf16 v[42:45], v[158:161], v[198:201], v[42:45]
	v_mfma_f32_16x16x32_bf16 v[38:41], v[158:161], v[190:193], v[38:41]
	v_mfma_f32_16x16x32_bf16 v[38:41], v[162:165], v[194:197], v[38:41]
	v_mfma_f32_16x16x32_bf16 v[26:29], v[162:165], v[186:189], v[26:29]
	v_mfma_f32_16x16x32_bf16 v[26:29], v[158:161], v[182:185], v[26:29]
	v_mfma_f32_16x16x32_bf16 v[114:117], v[166:169], v[182:185], v[114:117]
	v_mfma_f32_16x16x32_bf16 v[114:117], v[170:173], v[186:189], v[114:117]
	v_mfma_f32_16x16x32_bf16 v[118:121], v[170:173], v[194:197], v[118:121]
	v_mfma_f32_16x16x32_bf16 v[118:121], v[166:169], v[190:193], v[118:121]
	v_mfma_f32_16x16x32_bf16 v[122:125], v[166:169], v[198:201], v[122:125]
	v_mfma_f32_16x16x32_bf16 v[122:125], v[170:173], v[202:205], v[122:125]
	v_mfma_f32_16x16x32_bf16 v[126:129], v[170:173], v[210:213], v[126:129]
	v_mfma_f32_16x16x32_bf16 v[126:129], v[166:169], v[206:209], v[126:129]
	v_mfma_f32_16x16x32_bf16 v[62:65], v[174:177], v[206:209], v[62:65]
	v_mfma_f32_16x16x32_bf16 v[62:65], v[178:181], v[210:213], v[62:65]
	v_mfma_f32_16x16x32_bf16 v[58:61], v[178:181], v[202:205], v[58:61]
	v_mfma_f32_16x16x32_bf16 v[58:61], v[174:177], v[198:201], v[58:61]
	v_mfma_f32_16x16x32_bf16 v[54:57], v[174:177], v[190:193], v[54:57]
	v_mfma_f32_16x16x32_bf16 v[54:57], v[178:181], v[194:197], v[54:57]
	v_mfma_f32_16x16x32_bf16 v[50:53], v[178:181], v[186:189], v[50:53]
	v_mfma_f32_16x16x32_bf16 v[50:53], v[174:177], v[182:185], v[50:53]
	s_setprio 0
	s_barrier
	s_add_i32 s78, 0, 0x18000
	s_add_i32 s79, 0, 0x1c000
	ds_read_b128 v[150:153], v248
	ds_read_b128 v[154:157], v248 offset:1024
	ds_read_b128 v[158:161], v248 offset:2048
	ds_read_b128 v[162:165], v248 offset:3072
	ds_read_b128 v[166:169], v249
	ds_read_b128 v[170:173], v249 offset:1024
	ds_read_b128 v[174:177], v249 offset:2048
	ds_read_b128 v[178:181], v249 offset:3072
	ds_read_b128 v[182:185], v149 offset:32768
	ds_read_b128 v[186:189], v149 offset:33792
	ds_read_b128 v[190:193], v149 offset:34816
	ds_read_b128 v[194:197], v149 offset:35840
	ds_read_b128 v[198:201], v149 offset:36864
	ds_read_b128 v[202:205], v149 offset:37888
	ds_read_b128 v[206:209], v149 offset:38912
	ds_read_b128 v[210:213], v149 offset:39936
	s_add_u32 s50, s54, 0x40000
	s_addc_u32 s51, s55, 0
	s_mov_b32 m0, s62
	s_nop 0
	global_load_lds_dwordx4 v226, s[50:51]
	s_mov_b32 m0, s63
	s_nop 0
	global_load_lds_dwordx4 v230, s[50:51]
	s_waitcnt vmcnt(8)
	s_waitcnt lgkmcnt(0)
	s_barrier
	s_setprio 1
	v_mfma_f32_16x16x32_bf16 v[78:81], v[150:153], v[182:185], v[78:81]
	v_mfma_f32_16x16x32_bf16 v[78:81], v[154:157], v[186:189], v[78:81]
	v_mfma_f32_16x16x32_bf16 v[66:69], v[154:157], v[194:197], v[66:69]
	v_mfma_f32_16x16x32_bf16 v[66:69], v[150:153], v[190:193], v[66:69]
	v_mfma_f32_16x16x32_bf16 v[70:73], v[150:153], v[198:201], v[70:73]
	v_mfma_f32_16x16x32_bf16 v[70:73], v[154:157], v[202:205], v[70:73]
	v_mfma_f32_16x16x32_bf16 v[74:77], v[154:157], v[210:213], v[74:77]
	v_mfma_f32_16x16x32_bf16 v[74:77], v[150:153], v[206:209], v[74:77]
	v_mfma_f32_16x16x32_bf16 v[10:13], v[158:161], v[206:209], v[10:13]
	v_mfma_f32_16x16x32_bf16 v[10:13], v[162:165], v[210:213], v[10:13]
	v_mfma_f32_16x16x32_bf16 v[6:9], v[162:165], v[202:205], v[6:9]
	v_mfma_f32_16x16x32_bf16 v[6:9], v[158:161], v[198:201], v[6:9]
	v_mfma_f32_16x16x32_bf16 v[2:5], v[158:161], v[190:193], v[2:5]
	v_mfma_f32_16x16x32_bf16 v[2:5], v[162:165], v[194:197], v[2:5]
	v_mfma_f32_16x16x32_bf16 v[14:17], v[162:165], v[186:189], v[14:17]
	v_mfma_f32_16x16x32_bf16 v[14:17], v[158:161], v[182:185], v[14:17]
	v_mfma_f32_16x16x32_bf16 v[98:101], v[166:169], v[182:185], v[98:101]
	v_mfma_f32_16x16x32_bf16 v[98:101], v[170:173], v[186:189], v[98:101]
	v_mfma_f32_16x16x32_bf16 v[82:85], v[170:173], v[194:197], v[82:85]
	v_mfma_f32_16x16x32_bf16 v[82:85], v[166:169], v[190:193], v[82:85]
	v_mfma_f32_16x16x32_bf16 v[86:89], v[166:169], v[198:201], v[86:89]
	v_mfma_f32_16x16x32_bf16 v[86:89], v[170:173], v[202:205], v[86:89]
	v_mfma_f32_16x16x32_bf16 v[94:97], v[170:173], v[210:213], v[94:97]
	v_mfma_f32_16x16x32_bf16 v[94:97], v[166:169], v[206:209], v[94:97]
	v_mfma_f32_16x16x32_bf16 v[30:33], v[174:177], v[206:209], v[30:33]
	v_mfma_f32_16x16x32_bf16 v[30:33], v[178:181], v[210:213], v[30:33]
	v_mfma_f32_16x16x32_bf16 v[22:25], v[178:181], v[202:205], v[22:25]
	v_mfma_f32_16x16x32_bf16 v[22:25], v[174:177], v[198:201], v[22:25]
	v_mfma_f32_16x16x32_bf16 v[18:21], v[174:177], v[190:193], v[18:21]
	v_mfma_f32_16x16x32_bf16 v[18:21], v[178:181], v[194:197], v[18:21]
	v_mfma_f32_16x16x32_bf16 v[34:37], v[178:181], v[186:189], v[34:37]
	v_mfma_f32_16x16x32_bf16 v[34:37], v[174:177], v[182:185], v[34:37]
	s_setprio 0
	s_barrier
	ds_read_b128 v[182:185], v149 offset:49152
	ds_read_b128 v[186:189], v149 offset:50176
	ds_read_b128 v[190:193], v149 offset:51200
	ds_read_b128 v[194:197], v149 offset:52224
	ds_read_b128 v[198:201], v149 offset:53248
	ds_read_b128 v[202:205], v149 offset:54272
	ds_read_b128 v[206:209], v149 offset:55296
	ds_read_b128 v[210:213], v149 offset:56320
	s_add_u32 s98, s52, 0x80
	s_addc_u32 s99, s53, 0
	s_add_u32 s100, s54, 0x80
	s_addc_u32 s101, s55, 0
	s_add_i32 s50, s78, s15
	s_mov_b32 m0, s50
	s_nop 0
	global_load_lds_dwordx4 v228, s[98:99]
	s_add_i32 m0, s50, 0x2000
	s_add_u32 s50, s52, 0x40080
	s_addc_u32 s51, s53, 0
	global_load_lds_dwordx4 v232, s[98:99]
	s_add_i32 s52, s79, s15
	s_mov_b32 m0, s52
	s_nop 0
	global_load_lds_dwordx4 v228, s[50:51]
	s_add_i32 m0, s52, 0x2000
	s_nop 0
	global_load_lds_dwordx4 v232, s[50:51]
	s_mov_b32 m0, s68
	s_nop 0
	global_load_lds_dwordx4 v226, s[100:101]
	s_mov_b32 m0, s69
	s_nop 0
	global_load_lds_dwordx4 v230, s[100:101]
	s_waitcnt vmcnt(8)
	s_waitcnt lgkmcnt(0)
	s_barrier
	s_setprio 1
	v_mfma_f32_16x16x32_bf16 v[90:93], v[150:153], v[182:185], v[90:93]
	v_mfma_f32_16x16x32_bf16 v[90:93], v[154:157], v[186:189], v[90:93]
	v_mfma_f32_16x16x32_bf16 v[102:105], v[154:157], v[194:197], v[102:105]
	v_mfma_f32_16x16x32_bf16 v[102:105], v[150:153], v[190:193], v[102:105]
	v_mfma_f32_16x16x32_bf16 v[106:109], v[150:153], v[198:201], v[106:109]
	v_mfma_f32_16x16x32_bf16 v[106:109], v[154:157], v[202:205], v[106:109]
	v_mfma_f32_16x16x32_bf16 v[110:113], v[154:157], v[210:213], v[110:113]
	v_mfma_f32_16x16x32_bf16 v[110:113], v[150:153], v[206:209], v[110:113]
	v_mfma_f32_16x16x32_bf16 v[46:49], v[158:161], v[206:209], v[46:49]
	v_mfma_f32_16x16x32_bf16 v[46:49], v[162:165], v[210:213], v[46:49]
	v_mfma_f32_16x16x32_bf16 v[42:45], v[162:165], v[202:205], v[42:45]
	v_mfma_f32_16x16x32_bf16 v[42:45], v[158:161], v[198:201], v[42:45]
	v_mfma_f32_16x16x32_bf16 v[38:41], v[158:161], v[190:193], v[38:41]
	v_mfma_f32_16x16x32_bf16 v[38:41], v[162:165], v[194:197], v[38:41]
	v_mfma_f32_16x16x32_bf16 v[26:29], v[162:165], v[186:189], v[26:29]
	v_mfma_f32_16x16x32_bf16 v[26:29], v[158:161], v[182:185], v[26:29]
	v_mfma_f32_16x16x32_bf16 v[114:117], v[166:169], v[182:185], v[114:117]
	v_mfma_f32_16x16x32_bf16 v[114:117], v[170:173], v[186:189], v[114:117]
	v_mfma_f32_16x16x32_bf16 v[118:121], v[170:173], v[194:197], v[118:121]
	v_mfma_f32_16x16x32_bf16 v[118:121], v[166:169], v[190:193], v[118:121]
	v_mfma_f32_16x16x32_bf16 v[122:125], v[166:169], v[198:201], v[122:125]
	v_mfma_f32_16x16x32_bf16 v[122:125], v[170:173], v[202:205], v[122:125]
	v_mfma_f32_16x16x32_bf16 v[126:129], v[170:173], v[210:213], v[126:129]
	v_mfma_f32_16x16x32_bf16 v[126:129], v[166:169], v[206:209], v[126:129]
	v_mfma_f32_16x16x32_bf16 v[62:65], v[174:177], v[206:209], v[62:65]
	v_mfma_f32_16x16x32_bf16 v[62:65], v[178:181], v[210:213], v[62:65]
	v_mfma_f32_16x16x32_bf16 v[58:61], v[178:181], v[202:205], v[58:61]
	v_mfma_f32_16x16x32_bf16 v[58:61], v[174:177], v[198:201], v[58:61]
	v_mfma_f32_16x16x32_bf16 v[54:57], v[174:177], v[190:193], v[54:57]
	v_mfma_f32_16x16x32_bf16 v[54:57], v[178:181], v[194:197], v[54:57]
	v_mfma_f32_16x16x32_bf16 v[50:53], v[178:181], v[186:189], v[50:53]
	v_mfma_f32_16x16x32_bf16 v[50:53], v[174:177], v[182:185], v[50:53]
	s_setprio 0
	s_barrier
	s_add_u32 s34, s34, 0x100
	s_addc_u32 s35, s35, 0
	s_add_u32 s21, s21, 0x100
	s_addc_u32 s23, s23, 0
	s_cmp_ge_i32 s77, s66
	s_mov_b32 s52, s77
	s_cbranch_scc0 .LBB0_872
